# static s_setprio 1 for waves 4-7 during the attention phase (reset to 0 at phase exit)
# speedup vs baseline: 1.0138x; 1.0138x over previous
; #define LAS __attribute__((address_space(3)))
; __device__ __forceinline__ void attn_phase(LAS unsigned char* lds, int* counter, const bf16_t* __restrict__ P, const bf16_t* __restrict__ Qm, const bf16_t* __restrict__ Kmla, ...
;     LAS int* sunit = (LAS int*)(lds + MISC_OFF);
;     const int wid = wave0;
;     const int x0 = (int)((unsigned)__builtin_amdgcn_s_getreg((3 << 11) | 20) & 7u);
; #pragma nounroll
;     for (int xi = 0; xi < 8; ++xi) {
;     const int bq = (x0 + xi) & 7;
; __global__ void __launch_bounds__(NTHR, 2) hymba_fwd(KArgs a) {
;     ...
;             attn_phase(lds, (int*)(ws + WS_CTL) + 8 * l, P, (const bf16_t*)(ws + WS_QM), (const bf16_t*)(ws + WS_KMLA), (const bf16_t*)(ws + WS_VMLA), (const unsigned long long*)(ws + WS_MASK),
;                        (const bf16_t*)(ws + WS_OCMP), (const float*)(ws + WS_GATES), PIN(12) + l * 64, ((const float*)(ws + WS_CTL + 256))[2 * l], ((const float*)(ws + WS_CTL + 256))[2 * l + 1], hn, wave0);
.LBB0_663:
	s_and_b64 vcc, exec, s[4:5]
	s_cbranch_vccz .LBB0_756
	s_cmp_lt_u32 s55, 128
	s_cbranch_scc1 .Lattn_prio_skip
	s_setprio 1
.Lattn_prio_skip:
	v_readlane_b32 s12, v254, 44
	v_readlane_b32 s13, v254, 45
	s_and_b64 s[2:3], s[12:13], exec
	s_cselect_b32 s4, 8, 0
	s_lshl_b32 s2, s4, 2
	s_add_u32 s24, s8, s2
	s_addc_u32 s25, s9, 0
	s_add_u32 s26, s8, 0x146c1000
	s_addc_u32 s27, s9, 0
	s_add_u32 s28, s8, 0x15ec1000
	s_addc_u32 s29, s9, 0
	s_add_u32 s30, s8, 0x176c1000
	s_addc_u32 s31, s9, 0
	s_add_u32 s34, s8, 0x1c6c1000
	s_addc_u32 s35, s9, 0
	s_mov_b64 s[6:7], s[8:9]
	s_add_u32 s8, s6, 0x1c741000
	s_addc_u32 s9, s7, 0
	s_add_u32 s10, s6, 0x1c3c1000
	s_addc_u32 s11, s7, 0
	s_and_b64 s[2:3], s[12:13], exec
	s_cselect_b32 s12, 0x100, 0
	s_add_u32 s2, s6, s4
	s_addc_u32 s3, s7, 0
	global_load_dwordx2 v[0:1], v215, s[6:7] offset:3168
	global_load_dwordx2 v[180:181], v215, s[2:3] offset:256
	s_mov_b32 s13, 0
	v_readlane_b32 s68, v254, 7
	s_waitcnt vmcnt(1)
	v_lshl_add_u64 v[182:183], v[0:1], 0, s[12:13]
	s_getreg_b32 s12, hwreg(HW_REG_XCC_ID, 0, 4)
	v_readlane_b32 s2, v253, 58
	v_readlane_b32 s3, v254, 43
	s_nop 3
	s_and_b32 s3, s3, 7
	s_cmp_eq_u32 s2, 0x100
	s_cselect_b32 s12, s3, s12
	s_mov_b32 s2, 0
	s_nop 0
	v_writelane_b32 v255, s2, 62
	s_waitcnt vmcnt(0)
	v_sub_f32_e32 v181, 1.0, v181
	s_branch .LBB0_666

; __device__ __forceinline__ void attn_phase(LAS unsigned char* lds, int* counter, const bf16_t* __restrict__ P, const bf16_t* __restrict__ Qm, const bf16_t* __restrict__ Kmla, ...
;     ...
;     }
;     }
; }
.LBB0_755:
	s_setprio 0
	v_readlane_b32 s8, v254, 50
	s_mov_b64 s[14:15], -1
	s_mov_b64 s[2:3], 0
	s_mov_b32 s68, 0
	s_mov_b32 s6, 0
	v_readlane_b32 s9, v254, 51
